# grid barriers: waiting workgroups poll the top-level generation flag directly (no per-XCD relay hop)
# speedup vs baseline: 1.0083x; 1.0083x over previous
.LBB0_164:
	s_or_b64 exec, exec, s[8:9]
	v_cvt_f32_u32_e32 v4, v2
	s_waitcnt vmcnt(0)
	v_readfirstlane_b32 s6, v3
	s_add_u32 s4, s4, 0x2400
	s_addc_u32 s5, s5, 0
	s_add_u32 s98, s74, 0x3403500
	s_addc_u32 s99, s75, 0
	v_rcp_iflag_f32_e32 v4, v4
	v_add_u32_e32 v5, s6, v1
	v_mul_f32_e32 v3, 0x4f7ffffe, v4
	v_cvt_u32_f32_e32 v3, v3
	v_sub_u32_e32 v4, 0, v2
	v_mul_lo_u32 v1, v4, v3
	v_mul_hi_u32 v1, v3, v1
	v_add_u32_e32 v1, v3, v1
	v_mul_hi_u32 v1, v5, v1
	v_mul_lo_u32 v3, v1, v2
	v_sub_u32_e32 v3, v5, v3
	v_add_u32_e32 v4, 1, v1
	v_cmp_ge_u32_e32 vcc, v3, v2
	s_nop 1
	v_cndmask_b32_e32 v1, v1, v4, vcc
	v_sub_u32_e32 v4, v3, v2
	v_cndmask_b32_e32 v3, v3, v4, vcc
	v_add_u32_e32 v4, 1, v1
	v_cmp_ge_u32_e32 vcc, v3, v2
	v_add_u32_e32 v3, 1, v5
	s_nop 0
	v_cndmask_b32_e32 v1, v1, v4, vcc
	v_mul_lo_u32 v4, v2, v1
	v_add_u32_e32 v2, v4, v2
	v_cmp_ne_u32_e32 vcc, v3, v2
	s_and_saveexec_b64 s[6:7], vcc
	s_xor_b64 s[6:7], exec, s[6:7]
	s_cbranch_execz .LBB0_178
	s_waitcnt lgkmcnt(0)
	v_mov_b32_e32 v0, 0
	global_load_dword v2, v0, s[98:99] sc1
	s_waitcnt vmcnt(0)
	v_cmp_eq_u32_e32 vcc, v2, v1
	s_and_saveexec_b64 s[8:9], vcc
	s_cbranch_execz .LBB0_177
	s_mov_b32 s33, 1
	s_mov_b64 s[10:11], 0
	s_branch .LBB0_168

.LBB0_172:
	global_load_dword v2, v0, s[98:99] sc1
	s_add_i32 s33, s33, 1
	s_mov_b64 s[34:35], -1
	s_waitcnt vmcnt(0)
	v_cmp_ne_u32_e32 vcc, v2, v1
	s_orn2_b64 s[14:15], vcc, exec
	s_branch .LBB0_167

.LBB0_242:
	global_load_dword v2, v0, s[98:99] sc1
	s_add_i32 s33, s33, 1
	s_mov_b64 s[16:17], -1
	s_waitcnt vmcnt(0)
	v_cmp_ne_u32_e32 vcc, v2, v1
	s_orn2_b64 s[14:15], vcc, exec
	s_branch .LBB0_237

.LBB0_992:
	s_or_b64 exec, exec, s[8:9]
	v_cvt_f32_u32_e32 v4, v2
	s_waitcnt vmcnt(0)
	v_readfirstlane_b32 s6, v3
	s_add_u32 s4, s4, 0x2400
	s_addc_u32 s5, s5, 0
	s_add_u32 s98, s74, 0x3403500
	s_addc_u32 s99, s75, 0
	v_rcp_iflag_f32_e32 v4, v4
	v_add_u32_e32 v5, s6, v1
	v_mul_f32_e32 v3, 0x4f7ffffe, v4
	v_cvt_u32_f32_e32 v3, v3
	v_sub_u32_e32 v4, 0, v2
	v_mul_lo_u32 v1, v4, v3
	v_mul_hi_u32 v1, v3, v1
	v_add_u32_e32 v1, v3, v1
	v_mul_hi_u32 v1, v5, v1
	v_mul_lo_u32 v3, v1, v2
	v_sub_u32_e32 v3, v5, v3
	v_add_u32_e32 v4, 1, v1
	v_cmp_ge_u32_e32 vcc, v3, v2
	s_nop 1
	v_cndmask_b32_e32 v1, v1, v4, vcc
	v_sub_u32_e32 v4, v3, v2
	v_cndmask_b32_e32 v3, v3, v4, vcc
	v_add_u32_e32 v4, 1, v1
	v_cmp_ge_u32_e32 vcc, v3, v2
	v_add_u32_e32 v3, 1, v5
	s_nop 0
	v_cndmask_b32_e32 v1, v1, v4, vcc
	v_mul_lo_u32 v4, v2, v1
	v_add_u32_e32 v2, v4, v2
	v_cmp_ne_u32_e32 vcc, v3, v2
	s_and_saveexec_b64 s[6:7], vcc
	s_xor_b64 s[6:7], exec, s[6:7]
	s_cbranch_execz .LBB0_1006
	s_waitcnt lgkmcnt(0)
	v_mov_b32_e32 v0, 0
	global_load_dword v2, v0, s[98:99] sc1
	s_waitcnt vmcnt(0)
	v_cmp_eq_u32_e32 vcc, v2, v1
	s_and_saveexec_b64 s[8:9], vcc
	s_cbranch_execz .LBB0_1005
	s_mov_b32 s28, 1
	s_mov_b64 s[10:11], 0
	s_branch .LBB0_996

.LBB0_1000:
	global_load_dword v2, v0, s[98:99] sc1
	s_add_i32 s28, s28, 1
	s_mov_b64 s[16:17], -1
	s_waitcnt vmcnt(0)
	v_cmp_ne_u32_e32 vcc, v2, v1
	s_orn2_b64 s[14:15], vcc, exec
	s_branch .LBB0_995

.LBB0_1322:
	s_or_b64 exec, exec, s[8:9]
	v_cvt_f32_u32_e32 v4, v2
	s_waitcnt vmcnt(0)
	v_readfirstlane_b32 s6, v3
	s_add_u32 s4, s4, 0x2400
	s_addc_u32 s5, s5, 0
	s_add_u32 s98, s74, 0x3403500
	s_addc_u32 s99, s75, 0
	v_rcp_iflag_f32_e32 v4, v4
	v_add_u32_e32 v5, s6, v1
	v_mul_f32_e32 v3, 0x4f7ffffe, v4
	v_cvt_u32_f32_e32 v3, v3
	v_sub_u32_e32 v4, 0, v2
	v_mul_lo_u32 v1, v4, v3
	v_mul_hi_u32 v1, v3, v1
	v_add_u32_e32 v1, v3, v1
	v_mul_hi_u32 v1, v5, v1
	v_mul_lo_u32 v3, v1, v2
	v_sub_u32_e32 v3, v5, v3
	v_add_u32_e32 v4, 1, v1
	v_cmp_ge_u32_e32 vcc, v3, v2
	s_nop 1
	v_cndmask_b32_e32 v1, v1, v4, vcc
	v_sub_u32_e32 v4, v3, v2
	v_cndmask_b32_e32 v3, v3, v4, vcc
	v_add_u32_e32 v4, 1, v1
	v_cmp_ge_u32_e32 vcc, v3, v2
	v_add_u32_e32 v3, 1, v5
	s_nop 0
	v_cndmask_b32_e32 v1, v1, v4, vcc
	v_mul_lo_u32 v4, v2, v1
	v_add_u32_e32 v2, v4, v2
	v_cmp_ne_u32_e32 vcc, v3, v2
	s_and_saveexec_b64 s[6:7], vcc
	s_xor_b64 s[6:7], exec, s[6:7]
	s_cbranch_execz .LBB0_1336
	s_waitcnt lgkmcnt(0)
	v_mov_b32_e32 v0, 0
	global_load_dword v2, v0, s[98:99] sc1
	s_waitcnt vmcnt(0)
	v_cmp_eq_u32_e32 vcc, v2, v1
	s_and_saveexec_b64 s[8:9], vcc
	s_cbranch_execz .LBB0_1335
	s_mov_b32 s20, 1
	s_mov_b64 s[10:11], 0
	s_branch .LBB0_1326

.LBB0_1330:
	global_load_dword v2, v0, s[98:99] sc1
	s_add_i32 s20, s20, 1
	s_mov_b64 s[16:17], -1
	s_waitcnt vmcnt(0)
	v_cmp_ne_u32_e32 vcc, v2, v1
	s_orn2_b64 s[14:15], vcc, exec
	s_branch .LBB0_1325

	.amdhsa_kernel _Z6mk_fwd4Args
		.amdhsa_group_segment_fixed_size 0
		.amdhsa_private_segment_fixed_size 0
		.amdhsa_kernarg_size 488
		.amdhsa_user_sgpr_count 2
		.amdhsa_user_sgpr_dispatch_ptr 0
		.amdhsa_user_sgpr_queue_ptr 0
		.amdhsa_user_sgpr_kernarg_segment_ptr 1
		.amdhsa_user_sgpr_dispatch_id 0
		.amdhsa_user_sgpr_kernarg_preload_length 0
		.amdhsa_user_sgpr_kernarg_preload_offset 0
		.amdhsa_user_sgpr_private_segment_size 0
		.amdhsa_uses_dynamic_stack 0
		.amdhsa_enable_private_segment 0
		.amdhsa_system_sgpr_workgroup_id_x 1
		.amdhsa_system_sgpr_workgroup_id_y 0
		.amdhsa_system_sgpr_workgroup_id_z 0
		.amdhsa_system_sgpr_workgroup_info 0
		.amdhsa_system_vgpr_workitem_id 2
		.amdhsa_next_free_vgpr 256
		.amdhsa_next_free_sgpr 102
		.amdhsa_accum_offset 256
		.amdhsa_reserve_vcc 1
		.amdhsa_float_round_mode_32 0
		.amdhsa_float_round_mode_16_64 0
		.amdhsa_float_denorm_mode_32 3
		.amdhsa_float_denorm_mode_16_64 3
		.amdhsa_dx10_clamp 1
		.amdhsa_ieee_mode 1
		.amdhsa_fp16_overflow 0
		.amdhsa_tg_split 0
		.amdhsa_exception_fp_ieee_invalid_op 0
		.amdhsa_exception_fp_denorm_src 0
		.amdhsa_exception_fp_ieee_div_zero 0
		.amdhsa_exception_fp_ieee_overflow 0
		.amdhsa_exception_fp_ieee_underflow 0
		.amdhsa_exception_fp_ieee_inexact 0
		.amdhsa_exception_int_div_zero 0
	.end_amdhsa_kernel

amdhsa.kernels:
  - .agpr_count:     0
    .args:
      - .offset:         0
        .size:           232
        .value_kind:     by_value
      - .offset:         232
        .size:           4
        .value_kind:     hidden_block_count_x
      - .offset:         236
        .size:           4
        .value_kind:     hidden_block_count_y
      - .offset:         240
        .size:           4
        .value_kind:     hidden_block_count_z
      - .offset:         244
        .size:           2
        .value_kind:     hidden_group_size_x
      - .offset:         246
        .size:           2
        .value_kind:     hidden_group_size_y
      - .offset:         248
        .size:           2
        .value_kind:     hidden_group_size_z
      - .offset:         250
        .size:           2
        .value_kind:     hidden_remainder_x
      - .offset:         252
        .size:           2
        .value_kind:     hidden_remainder_y
      - .offset:         254
        .size:           2
        .value_kind:     hidden_remainder_z
      - .offset:         272
        .size:           8
        .value_kind:     hidden_global_offset_x
      - .offset:         280
        .size:           8
        .value_kind:     hidden_global_offset_y
      - .offset:         288
        .size:           8
        .value_kind:     hidden_global_offset_z
      - .offset:         296
        .size:           2
        .value_kind:     hidden_grid_dims
      - .offset:         320
        .size:           8
        .value_kind:     hidden_multigrid_sync_arg
      - .offset:         352
        .size:           4
        .value_kind:     hidden_dynamic_lds_size
    .group_segment_fixed_size: 0
    .kernarg_segment_align: 8
    .kernarg_segment_size: 488
    .language:       OpenCL C
    .language_version:
      - 2
      - 0
    .max_flat_workgroup_size: 512
    .name:           _Z6mk_fwd4Args
    .private_segment_fixed_size: 0
    .sgpr_count:     108
    .sgpr_spill_count: 84
    .symbol:         _Z6mk_fwd4Args.kd
    .uniform_work_group_size: 1
    .uses_dynamic_stack: false
    .vgpr_count:     256
    .vgpr_spill_count: 0
    .wavefront_size: 64
